# half move: only the second half of the qk epilogue (accumulator multiply, masks, stores) runs after the step-4 barrier
# speedup vs baseline: 1.0122x; 1.0122x over previous
.LBB0_137:
	v_lshl_or_b32 v21, s6, 5, v94
	v_lshl_or_b32 v22, s52, 5, v25
	v_lshl_add_u32 v18, v21, 2, 0
	v_lshl_add_u32 v19, v22, 2, 0
	v_add_u32_e32 v18, 0x24900, v18
	v_add_u32_e32 v19, 0x24900, v19
	ds_read_b32 v20, v18
	ds_read_b128 v[106:109], v19
	ds_read_b128 v[110:113], v19 offset:32
	ds_read_b128 v[114:117], v19 offset:64
	ds_read_b128 v[118:121], v19 offset:96
	v_sub_u32_e32 v21, v21, v22
	v_add_u32_e32 v21, 1, v21
	s_lshl_b32 s6, s6, 12
	s_lshl_b32 s7, s52, 11
	s_or_b32 s6, s6, s7
	v_lshl_or_b32 v22, v93, 4, s6
	s_add_i32 s6, s51, 0x8000
	v_add_u32_e32 v18, s6, v22
	s_add_i32 s6, s51, 0x8400
	v_add_u32_e32 v22, s6, v22
	s_waitcnt lgkmcnt(0)
	v_sub_f32_e32 v106, v20, v106
	v_sub_f32_e32 v107, v20, v107
	v_sub_f32_e32 v108, v20, v108
	v_sub_f32_e32 v109, v20, v109
	v_sub_f32_e32 v110, v20, v110
	v_sub_f32_e32 v111, v20, v111
	v_sub_f32_e32 v112, v20, v112
	v_sub_f32_e32 v113, v20, v113
	v_sub_f32_e32 v114, v20, v114
	v_sub_f32_e32 v115, v20, v115
	v_sub_f32_e32 v116, v20, v116
	v_sub_f32_e32 v117, v20, v117
	v_sub_f32_e32 v118, v20, v118
	v_sub_f32_e32 v119, v20, v119
	v_sub_f32_e32 v120, v20, v120
	v_sub_f32_e32 v121, v20, v121
	v_mul_f32_e32 v106, 0x3fb8aa3b, v106
	v_mul_f32_e32 v107, 0x3fb8aa3b, v107
	v_mul_f32_e32 v108, 0x3fb8aa3b, v108
	v_mul_f32_e32 v109, 0x3fb8aa3b, v109
	v_mul_f32_e32 v110, 0x3fb8aa3b, v110
	v_mul_f32_e32 v111, 0x3fb8aa3b, v111
	v_mul_f32_e32 v112, 0x3fb8aa3b, v112
	v_mul_f32_e32 v113, 0x3fb8aa3b, v113
	v_mul_f32_e32 v114, 0x3fb8aa3b, v114
	v_mul_f32_e32 v115, 0x3fb8aa3b, v115
	v_mul_f32_e32 v116, 0x3fb8aa3b, v116
	v_mul_f32_e32 v117, 0x3fb8aa3b, v117
	v_mul_f32_e32 v118, 0x3fb8aa3b, v118
	v_mul_f32_e32 v119, 0x3fb8aa3b, v119
	v_mul_f32_e32 v120, 0x3fb8aa3b, v120
	v_mul_f32_e32 v121, 0x3fb8aa3b, v121
	v_exp_f32_e32 v106, v106
	v_exp_f32_e32 v107, v107
	v_exp_f32_e32 v108, v108
	v_exp_f32_e32 v109, v109
	v_exp_f32_e32 v110, v110
	v_exp_f32_e32 v111, v111
	v_exp_f32_e32 v112, v112
	v_exp_f32_e32 v113, v113
	v_exp_f32_e32 v114, v114
	v_exp_f32_e32 v115, v115
	v_exp_f32_e32 v116, v116
	v_exp_f32_e32 v117, v117
	v_exp_f32_e32 v118, v118
	v_exp_f32_e32 v119, v119
	v_exp_f32_e32 v120, v120
	v_exp_f32_e32 v121, v121
	s_barrier
	v_mul_f32_e32 v106, v2, v106
	v_mul_f32_e32 v107, v3, v107
	v_mul_f32_e32 v108, v4, v108
	v_mul_f32_e32 v109, v5, v109
	v_mul_f32_e32 v110, v6, v110
	v_mul_f32_e32 v111, v7, v111
	v_mul_f32_e32 v112, v8, v112
	v_mul_f32_e32 v113, v9, v113
	v_mul_f32_e32 v114, v10, v114
	v_mul_f32_e32 v115, v11, v115
	v_mul_f32_e32 v116, v12, v116
	v_mul_f32_e32 v117, v13, v117
	v_mul_f32_e32 v118, v14, v118
	v_mul_f32_e32 v119, v15, v119
	v_mul_f32_e32 v120, v16, v120
	v_mul_f32_e32 v121, v17, v121
	v_cmp_lt_i32_e32 vcc, 0, v21
	v_cmp_lt_i32_e64 s[28:29], 1, v21
	v_cmp_lt_i32_e64 s[6:7], 2, v21
	v_cndmask_b32_e32 v106, 0, v106, vcc
	v_cmp_lt_i32_e32 vcc, 3, v21
	v_cndmask_b32_e64 v107, 0, v107, s[28:29]
	v_cmp_lt_i32_e64 s[28:29], 8, v21
	v_cndmask_b32_e64 v108, 0, v108, s[6:7]
	v_cmp_lt_i32_e64 s[6:7], 9, v21
	v_cndmask_b32_e32 v109, 0, v109, vcc
	v_cmp_lt_i32_e32 vcc, 10, v21
	v_cndmask_b32_e64 v110, 0, v110, s[28:29]
	v_cmp_lt_i32_e64 s[28:29], 11, v21
	v_cndmask_b32_e64 v111, 0, v111, s[6:7]
	v_cmp_lt_i32_e64 s[6:7], 16, v21
	v_cndmask_b32_e32 v112, 0, v112, vcc
	v_cmp_lt_i32_e32 vcc, 17, v21
	v_cndmask_b32_e64 v113, 0, v113, s[28:29]
	v_cmp_lt_i32_e64 s[28:29], 18, v21
	v_cndmask_b32_e64 v114, 0, v114, s[6:7]
	v_cmp_lt_i32_e64 s[6:7], 19, v21
	v_cndmask_b32_e32 v115, 0, v115, vcc
	v_cmp_lt_i32_e32 vcc, 24, v21
	v_cndmask_b32_e64 v116, 0, v116, s[28:29]
	v_cmp_lt_i32_e64 s[28:29], 25, v21
	v_cndmask_b32_e64 v117, 0, v117, s[6:7]
	v_cmp_lt_i32_e64 s[6:7], 26, v21
	v_cndmask_b32_e32 v118, 0, v118, vcc
	v_cmp_lt_i32_e32 vcc, 27, v21
	v_cndmask_b32_e64 v119, 0, v119, s[28:29]
	v_cndmask_b32_e64 v120, 0, v120, s[6:7]
	v_cndmask_b32_e32 v121, 0, v121, vcc
	v_cvt_pk_bf16_f32 v122, v106, v107
	v_cvt_pk_bf16_f32 v123, v108, v109
	v_cvt_pk_bf16_f32 v124, v110, v111
	v_cvt_pk_bf16_f32 v125, v112, v113
	v_cvt_pk_bf16_f32 v126, v114, v115
	v_cvt_pk_bf16_f32 v127, v116, v117
	v_cvt_pk_bf16_f32 v128, v118, v119
	v_cvt_pk_bf16_f32 v129, v120, v121
	buffer_store_dwordx4 v[122:125], v18, s[72:75], 0 offen sc1
	buffer_store_dwordx4 v[126:129], v22, s[72:75], 0 offen sc1
	v_lshl_or_b32 v96, s52, 5, v94
	s_branch .Lqk_after
